# v87 + attention loop 1: exp/sum/cvt of P slice k+1 issued in the shadow of PV MFMAs of slice k (intra-wave overlap)
# baseline (speedup 1.0000x reference)
; DI unsigned pk2(float a, float b) { f32x2 f = {a, b}; bf16v2 r = __builtin_convertvector(f, bf16v2); return __builtin_bit_cast(unsigned, r); }
; #define VLD(dst, j, dt) do { LAS unsigned char* va_ = vb + (32 * (dt) + n) * VROW + (16 * (j) + 4 * g) * 2; const u32x2 lo_ = *(const LAS u32x2*)(va_), hi_ = *(const LAS u32x2*)(va_ + 16); dst = (u32x4){lo_.x, lo_.y, hi_.x, hi_.y}; } while (0)
; DI void attn_unit(LAS unsigned char* lds, int wid, int b, int h, int qb) {
;     ...
;             const float mnew = fmaxf(mrow, mx), alpha = __builtin_amdgcn_exp2f(mrow - mnew); mrow = mnew;
;             float ls = 0.f;
; #pragma unroll
;             for (int i = 0; i < 16; ++i) { s0[i] = __builtin_amdgcn_exp2f(s0[i] - mnew); s1[i] = __builtin_amdgcn_exp2f(s1[i] - mnew); ls += s0[i] + s1[i]; }
;             lrow = lrow * alpha + ls;
;             if (__builtin_amdgcn_ballot_w64(alpha != 1.f) != 0ull) {
; #pragma unroll
;                 for (int dt = 0; dt < 4; ++dt)
; #pragma unroll
;                     for (int i = 0; i < 16; ++i) o[dt][i] *= alpha;
;             }
;             bf16x8 pf[4];
; #pragma unroll
;             for (int jj = 0; jj < 2; ++jj) { u32x4 w0, w1;
;                 w0.x = pk2(s0[8 * jj + 0], s0[8 * jj + 1]); w0.y = pk2(s0[8 * jj + 2], s0[8 * jj + 3]); w0.z = pk2(s0[8 * jj + 4], s0[8 * jj + 5]); w0.w = pk2(s0[8 * jj + 6], s0[8 * jj + 7]);
;                 w1.x = pk2(s1[8 * jj + 0], s1[8 * jj + 1]); w1.y = pk2(s1[8 * jj + 2], s1[8 * jj + 3]); w1.z = pk2(s1[8 * jj + 4], s1[8 * jj + 5]); w1.w = pk2(s1[8 * jj + 6], s1[8 * jj + 7]);
;                 pf[jj] = __builtin_bit_cast(bf16x8, w0); pf[2 + jj] = __builtin_bit_cast(bf16x8, w1); }
; #pragma unroll
;             for (int j = 0; j < 4; ++j) {
;                 if (j < 3) {
; #pragma unroll
;                     for (int dt = 0; dt < 4; ++dt) VLD(vf[(j + 1) & 1][dt], j + 1, dt);
;                 }
; #pragma unroll
;                 for (int dt = 0; dt < 4; ++dt) o[dt] = __builtin_amdgcn_mfma_f32_32x32x16_bf16(__builtin_bit_cast(bf16x8, vf[j & 1][dt]), pf[j], o[dt], 0, 0, 0);
;                 __builtin_amdgcn_sched_barrier(0); }
.LBB0_1082:
	v_exp_f32_e32 v66, v66
	v_exp_f32_e32 v67, v67
	v_exp_f32_e32 v68, v68
	v_exp_f32_e32 v69, v69
	v_exp_f32_e32 v70, v70
	v_exp_f32_e32 v71, v71
	v_exp_f32_e32 v72, v72
	v_exp_f32_e32 v73, v73
	v_add_f32_e32 v208, v66, v67
	v_add_f32_e32 v209, v68, v69
	v_add_f32_e32 v208, v208, v209
	v_add_f32_e32 v209, v70, v71
	v_add_f32_e32 v208, v208, v209
	v_add_f32_e32 v209, v72, v73
	v_add_f32_e32 v208, v208, v209
	v_cvt_pk_bf16_f32 v66, v66, v67
	v_cvt_pk_bf16_f32 v67, v68, v69
	v_cvt_pk_bf16_f32 v68, v70, v71
	v_cvt_pk_bf16_f32 v69, v72, v73
	ds_read2_b64 v[242:245], v204 offset0:132 offset1:134
	ds_read2_b64 v[246:249], v205 offset0:164 offset1:166
	ds_read2_b64 v[250:253], v206 offset0:196 offset1:198
	ds_read2_b64 v[232:235], v207 offset0:228 offset1:230
	v_exp_f32_e32 v74, v74
	v_exp_f32_e32 v75, v75
	v_mfma_f32_32x32x16_bf16 v[50:65], v[166:169], v[66:69], v[50:65]
	v_exp_f32_e32 v76, v76
	v_exp_f32_e32 v77, v77
	v_exp_f32_e32 v78, v78
	s_waitcnt lgkmcnt(6)
	v_mfma_f32_32x32x16_bf16 v[34:49], v[178:181], v[66:69], v[34:49]
	v_exp_f32_e32 v79, v79
	v_exp_f32_e32 v80, v80
	v_exp_f32_e32 v81, v81
	v_add_f32_e32 v209, v74, v75
	v_add_f32_e32 v208, v208, v209
	s_waitcnt lgkmcnt(5)
	v_mfma_f32_32x32x16_bf16 v[18:33], v[174:177], v[66:69], v[18:33]
	v_add_f32_e32 v209, v76, v77
	v_add_f32_e32 v208, v208, v209
	v_add_f32_e32 v209, v78, v79
	v_add_f32_e32 v208, v208, v209
	s_waitcnt lgkmcnt(4)
	v_mfma_f32_32x32x16_bf16 v[2:17], v[170:173], v[66:69], v[2:17]
	v_add_f32_e32 v209, v80, v81
	v_add_f32_e32 v208, v208, v209
	v_cvt_pk_bf16_f32 v74, v74, v75
	v_cvt_pk_bf16_f32 v75, v76, v77
	v_cvt_pk_bf16_f32 v76, v78, v79
	v_cvt_pk_bf16_f32 v77, v80, v81
	ds_read2_b64 v[166:169], v204 offset0:136 offset1:138
	ds_read2_b64 v[178:181], v205 offset0:168 offset1:170
	ds_read2_b64 v[174:177], v206 offset0:200 offset1:202
	ds_read2_b64 v[170:173], v207 offset0:232 offset1:234
	v_exp_f32_e32 v82, v82
	v_exp_f32_e32 v83, v83
	s_waitcnt lgkmcnt(7)
	v_mfma_f32_32x32x16_bf16 v[50:65], v[242:245], v[74:77], v[50:65]
	v_exp_f32_e32 v84, v84
	v_exp_f32_e32 v85, v85
	v_exp_f32_e32 v86, v86
	s_waitcnt lgkmcnt(6)
	v_mfma_f32_32x32x16_bf16 v[34:49], v[246:249], v[74:77], v[34:49]
	v_exp_f32_e32 v87, v87
	v_exp_f32_e32 v88, v88
	v_exp_f32_e32 v89, v89
	v_add_f32_e32 v209, v82, v83
	v_add_f32_e32 v208, v208, v209
	s_waitcnt lgkmcnt(5)
	v_mfma_f32_32x32x16_bf16 v[18:33], v[250:253], v[74:77], v[18:33]
	v_add_f32_e32 v209, v84, v85
	v_add_f32_e32 v208, v208, v209
	v_add_f32_e32 v209, v86, v87
	v_add_f32_e32 v208, v208, v209
	s_waitcnt lgkmcnt(4)
	v_mfma_f32_32x32x16_bf16 v[2:17], v[232:235], v[74:77], v[2:17]
	v_add_f32_e32 v209, v88, v89
	v_add_f32_e32 v208, v208, v209
	v_cvt_pk_bf16_f32 v70, v82, v83
	v_cvt_pk_bf16_f32 v71, v84, v85
	v_cvt_pk_bf16_f32 v72, v86, v87
	v_cvt_pk_bf16_f32 v73, v88, v89
	ds_read2_b64 v[242:245], v204 offset0:140 offset1:142
	ds_read2_b64 v[246:249], v205 offset0:172 offset1:174
	ds_read2_b64 v[250:253], v206 offset0:204 offset1:206
	ds_read2_b64 v[232:235], v207 offset0:236 offset1:238
	v_exp_f32_e32 v90, v90
	v_exp_f32_e32 v91, v91
	s_waitcnt lgkmcnt(7)
	v_mfma_f32_32x32x16_bf16 v[50:65], v[166:169], v[70:73], v[50:65]
	v_exp_f32_e32 v92, v92
	v_exp_f32_e32 v93, v93
	v_exp_f32_e32 v94, v94
	s_waitcnt lgkmcnt(6)
	v_mfma_f32_32x32x16_bf16 v[34:49], v[178:181], v[70:73], v[34:49]
	v_exp_f32_e32 v95, v95
	v_exp_f32_e32 v96, v96
	v_exp_f32_e32 v97, v97
	v_add_f32_e32 v209, v90, v91
	v_add_f32_e32 v208, v208, v209
	s_waitcnt lgkmcnt(5)
	v_mfma_f32_32x32x16_bf16 v[18:33], v[174:177], v[70:73], v[18:33]
	v_add_f32_e32 v209, v92, v93
	v_add_f32_e32 v208, v208, v209
	v_add_f32_e32 v209, v94, v95
	v_add_f32_e32 v208, v208, v209
	s_waitcnt lgkmcnt(4)
	v_mfma_f32_32x32x16_bf16 v[2:17], v[170:173], v[70:73], v[2:17]
	v_add_f32_e32 v209, v96, v97
	v_add_f32_e32 v208, v208, v209
	v_cvt_pk_bf16_f32 v78, v90, v91
	v_cvt_pk_bf16_f32 v79, v92, v93
	v_cvt_pk_bf16_f32 v80, v94, v95
	v_cvt_pk_bf16_f32 v81, v96, v97
	v_fma_f32 v187, v187, v196, v208
	s_nop 1
	s_waitcnt lgkmcnt(3)
	v_mfma_f32_32x32x16_bf16 v[50:65], v[242:245], v[78:81], v[50:65]
	s_waitcnt lgkmcnt(2)
	v_mfma_f32_32x32x16_bf16 v[34:49], v[246:249], v[78:81], v[34:49]
	s_waitcnt lgkmcnt(1)
	v_mfma_f32_32x32x16_bf16 v[18:33], v[250:253], v[78:81], v[18:33]
	s_waitcnt lgkmcnt(0)
	v_mfma_f32_32x32x16_bf16 v[2:17], v[232:235], v[78:81], v[2:17]
	s_branch .LBB0_1084
